# attn unmasked loop: K loads hoisted to loop top, V-frag reads 4 deep, K ds_writes moved under PV MFMAs
# speedup vs baseline: 1.0026x; 1.0026x over previous
; __device__ __forceinline__ void unit(LAS unsigned char* lds, int b, int h, int qb, const bf16_t* Q, const bf16_t* Kn, const bf16_t* Kr, const bf16_t* VT, const bf16_t* proj, bf16_t* ymix, int wv) {
;     ...
;     f32x16 o[4];
; #pragma unroll
;     for (int i = 0; i < 4; ++i) o[i] = (f32x16){0, 0, 0, 0, 0, 0, 0, 0, 0, 0, 0, 0, 0, 0, 0, 0};
;     float mrun = -INFINITY, lrun = 0.f;
;     const int qidx = q0 + 32 * wave + l32;
;     f32x16 p0, p1; bf16x8 pf[2][2];
.LBB0_612:
	s_sub_i32 s12, s58, 32
	s_lshl_b64 s[14:15], s[12:13], 11
	s_mov_b32 s59, s13
	v_lshl_add_u64 v[232:233], v[208:209], 0, s[14:15]
	s_lshl_b64 s[14:15], s[58:59], 11
	global_load_dwordx4 v[176:179], v[232:233], off
	v_lshl_add_u64 v[232:233], v[208:209], 0, s[14:15]
	s_lshl_b64 s[14:15], s[12:13], 7
	global_load_dwordx4 v[184:187], v[232:233], off
	v_lshl_add_u64 v[232:233], v[210:211], 0, s[14:15]
	global_load_dwordx4 v[188:191], v[232:233], off
	v_add_u32_e32 v0, s60, v215
	ds_read_b128 v[2:5], v0
	ds_read_b128 v[6:9], v0 offset:32
	v_mov_b64_e32 v[126:127], v[94:95]
	v_mov_b64_e32 v[124:125], v[92:93]
	v_mov_b64_e32 v[122:123], v[90:91]
	s_waitcnt lgkmcnt(1)
	v_mfma_f32_32x32x16_bf16 v[96:111], v[2:5], v[128:131], v[80:95]
	ds_read_b128 v[2:5], v0 offset:12800
	ds_read_b128 v[10:13], v0 offset:12832
	v_mov_b64_e32 v[120:121], v[88:89]
	v_mov_b64_e32 v[118:119], v[86:87]
	v_mov_b64_e32 v[116:117], v[84:85]
	v_mov_b64_e32 v[114:115], v[82:83]
	v_mov_b64_e32 v[112:113], v[80:81]
	s_waitcnt lgkmcnt(2)
	v_mfma_f32_32x32x16_bf16 v[96:111], v[6:9], v[132:135], v[96:111]
	s_mov_b32 s71, s9
	s_mov_b32 s72, s8
	s_waitcnt lgkmcnt(1)
	v_mfma_f32_32x32x16_bf16 v[112:127], v[2:5], v[128:131], v[112:127]
	ds_read_b128 v[2:5], v0 offset:64
	ds_read_b128 v[6:9], v0 offset:96
	s_waitcnt lgkmcnt(2)
	v_mfma_f32_32x32x16_bf16 v[112:127], v[10:13], v[132:135], v[112:127]
	s_waitcnt lgkmcnt(1)
	v_mfma_f32_32x32x16_bf16 v[96:111], v[2:5], v[136:139], v[96:111]
	ds_read_b128 v[2:5], v0 offset:12864
	ds_read_b128 v[10:13], v0 offset:12896
	s_waitcnt lgkmcnt(1)
	v_mfma_f32_32x32x16_bf16 v[112:127], v[2:5], v[136:139], v[112:127]
	v_mfma_f32_32x32x16_bf16 v[96:111], v[6:9], v[140:143], v[96:111]
	ds_read_b128 v[2:5], v0 offset:128
	ds_read_b128 v[6:9], v0 offset:160
	s_waitcnt lgkmcnt(2)
	v_mfma_f32_32x32x16_bf16 v[112:127], v[10:13], v[140:143], v[112:127]
	s_waitcnt lgkmcnt(1)
	v_mfma_f32_32x32x16_bf16 v[96:111], v[2:5], v[144:147], v[96:111]
	ds_read_b128 v[2:5], v0 offset:12928
	ds_read_b128 v[10:13], v0 offset:12960
	s_waitcnt lgkmcnt(1)
	v_mfma_f32_32x32x16_bf16 v[112:127], v[2:5], v[144:147], v[112:127]
	v_mfma_f32_32x32x16_bf16 v[96:111], v[6:9], v[148:151], v[96:111]
	ds_read_b128 v[2:5], v0 offset:192
	ds_read_b128 v[6:9], v0 offset:224
	s_waitcnt lgkmcnt(2)
	v_mfma_f32_32x32x16_bf16 v[112:127], v[10:13], v[148:151], v[112:127]
	s_waitcnt lgkmcnt(1)
	v_mfma_f32_32x32x16_bf16 v[96:111], v[2:5], v[152:155], v[96:111]
	ds_read_b128 v[2:5], v0 offset:12992
	ds_read_b128 v[10:13], v0 offset:13024
	s_waitcnt lgkmcnt(1)
	v_mfma_f32_32x32x16_bf16 v[112:127], v[2:5], v[152:155], v[112:127]
	v_mfma_f32_32x32x16_bf16 v[96:111], v[6:9], v[156:159], v[96:111]
	ds_read_b128 v[2:5], v0 offset:256
	ds_read_b128 v[6:9], v0 offset:288
	s_waitcnt lgkmcnt(2)
	v_mfma_f32_32x32x16_bf16 v[112:127], v[10:13], v[156:159], v[112:127]
	s_waitcnt lgkmcnt(1)
	v_mfma_f32_32x32x16_bf16 v[96:111], v[2:5], v[160:163], v[96:111]
	ds_read_b128 v[2:5], v0 offset:13056
	ds_read_b128 v[10:13], v0 offset:13088
	s_waitcnt lgkmcnt(1)
	v_mfma_f32_32x32x16_bf16 v[112:127], v[2:5], v[160:163], v[112:127]
	ds_read_b128 v[2:5], v0 offset:320
	v_mfma_f32_32x32x16_bf16 v[96:111], v[6:9], v[164:167], v[96:111]
	s_waitcnt lgkmcnt(1)
	v_mfma_f32_32x32x16_bf16 v[112:127], v[10:13], v[164:167], v[112:127]
	ds_read_b128 v[6:9], v0 offset:13120
	ds_read_b128 v[10:13], v0 offset:352
	s_waitcnt lgkmcnt(2)
	v_mfma_f32_32x32x16_bf16 v[96:111], v[2:5], v[168:171], v[96:111]
	s_add_i32 s12, s58, 0xffffffa0
	ds_read_b128 v[230:233], v0 offset:13152
	s_waitcnt lgkmcnt(2)
	v_mfma_f32_32x32x16_bf16 v[112:127], v[6:9], v[168:171], v[112:127]
	s_lshl_b64 s[14:15], s[12:13], 1
	v_lshl_add_u64 v[8:9], v[218:219], 0, s[14:15]
	v_lshl_add_u64 v[2:3], v[206:207], 0, s[14:15]
	global_load_dwordx4 v[2:5], v[2:3], off
	s_nop 0
	s_nop 0
	global_load_dwordx4 v[6:9], v[8:9], off
	s_waitcnt lgkmcnt(1)
	v_mfma_f32_32x32x16_bf16 v[96:111], v[10:13], v[172:175], v[96:111]
	s_waitcnt lgkmcnt(0)
	v_mfma_f32_32x32x16_bf16 v[112:127], v[230:233], v[172:175], v[112:127]
	s_add_i32 s8, s9, 0
	s_add_i32 s8, s8, 0x12c00
	v_add_u32_e32 v0, s8, v227
	v_add_u32_e32 v231, v0, v226
	v_add_u32_e32 v229, 0x1000, v231
	v_add_u32_e32 v230, 0x2000, v231
	v_add_u32_e32 v252, 0x3000, v231
	ds_read2_b64 v[234:237], v231 offset1:2
	ds_read2_b64 v[238:241], v229 offset0:32 offset1:34
	ds_read2_b64 v[244:247], v230 offset0:64 offset1:66
	ds_read2_b64 v[248:251], v252 offset0:96 offset1:98
	s_nop 2
	v_max_f32_e32 v0, v96, v96
	v_max_f32_e32 v0, 0xff800000, v0
	v_max3_f32 v0, v0, v97, v98
	s_waitcnt lgkmcnt(3)
	v_mfma_f32_32x32x16_bf16 v[64:79], v[234:237], v[200:203], v[64:79]
	ds_read2_b64 v[234:237], v231 offset0:4 offset1:6
	v_max3_f32 v10, v112, s64, v113
	v_max3_f32 v14, v10, v114, v115
	s_waitcnt lgkmcnt(3)
	v_mfma_f32_32x32x16_bf16 v[48:63], v[238:241], v[200:203], v[48:63]
	ds_read2_b64 v[238:241], v229 offset0:36 offset1:38
	v_max3_f32 v0, v0, v99, v100
	v_max3_f32 v14, v14, v116, v117
	v_max3_f32 v0, v0, v101, v102
	v_max3_f32 v14, v14, v118, v119
	s_waitcnt lgkmcnt(3)
	v_mfma_f32_32x32x16_bf16 v[32:47], v[244:247], v[200:203], v[32:47]
	ds_read2_b64 v[244:247], v230 offset0:68 offset1:70
	v_max3_f32 v0, v0, v103, v104
	v_max3_f32 v14, v14, v120, v121
	v_max3_f32 v0, v0, v105, v106
	v_max3_f32 v14, v14, v122, v123
	s_waitcnt lgkmcnt(3)
	v_mfma_f32_32x32x16_bf16 v[16:31], v[248:251], v[200:203], v[16:31]
	ds_read2_b64 v[248:251], v252 offset0:100 offset1:102
	v_max3_f32 v0, v0, v107, v108
	v_max3_f32 v10, v14, v124, v125
	v_max3_f32 v0, v0, v109, v110
	v_max3_f32 v14, v10, v126, v127
	v_max3_f32 v0, v0, v111, v14
	v_mov_b32_e32 v14, v222
	s_waitcnt lgkmcnt(3)
	v_mfma_f32_32x32x16_bf16 v[64:79], v[234:237], v[196:199], v[64:79]
	ds_read2_b64 v[234:237], v231 offset0:8 offset1:10
	v_lshlrev_b32_e32 v14, 2, v14
	v_xor_b32_e32 v14, 0x80, v14
	ds_bpermute_b32 v14, v14, v0
	s_waitcnt lgkmcnt(0)
	v_max_f32_e32 v14, v14, v14
	v_max_f32_e32 v0, v0, v14
	v_cmp_lt_f32_e32 vcc, s65, v0
	s_cbranch_vccz .LBB0_614
	v_max_f32_e32 v0, v0, v0
	v_max_f32_e32 v0, 0, v0
	v_add_f32_e32 v217, v217, v0
	v_pk_add_f32 v[96:97], v[96:97], v[0:1] op_sel_hi:[1,0] neg_lo:[0,1] neg_hi:[0,1]
	v_pk_add_f32 v[112:113], v[112:113], v[0:1] op_sel_hi:[1,0] neg_lo:[0,1] neg_hi:[0,1]
	v_pk_add_f32 v[98:99], v[98:99], v[0:1] op_sel_hi:[1,0] neg_lo:[0,1] neg_hi:[0,1]
	v_pk_add_f32 v[114:115], v[114:115], v[0:1] op_sel_hi:[1,0] neg_lo:[0,1] neg_hi:[0,1]
	v_pk_add_f32 v[100:101], v[100:101], v[0:1] op_sel_hi:[1,0] neg_lo:[0,1] neg_hi:[0,1]
	v_pk_add_f32 v[116:117], v[116:117], v[0:1] op_sel_hi:[1,0] neg_lo:[0,1] neg_hi:[0,1]
	v_pk_add_f32 v[102:103], v[102:103], v[0:1] op_sel_hi:[1,0] neg_lo:[0,1] neg_hi:[0,1]
	v_pk_add_f32 v[118:119], v[118:119], v[0:1] op_sel_hi:[1,0] neg_lo:[0,1] neg_hi:[0,1]
	v_pk_add_f32 v[104:105], v[104:105], v[0:1] op_sel_hi:[1,0] neg_lo:[0,1] neg_hi:[0,1]
	v_pk_add_f32 v[120:121], v[120:121], v[0:1] op_sel_hi:[1,0] neg_lo:[0,1] neg_hi:[0,1]
	v_pk_add_f32 v[106:107], v[106:107], v[0:1] op_sel_hi:[1,0] neg_lo:[0,1] neg_hi:[0,1]
	v_pk_add_f32 v[122:123], v[122:123], v[0:1] op_sel_hi:[1,0] neg_lo:[0,1] neg_hi:[0,1]
	v_pk_add_f32 v[108:109], v[108:109], v[0:1] op_sel_hi:[1,0] neg_lo:[0,1] neg_hi:[0,1]
	v_pk_add_f32 v[124:125], v[124:125], v[0:1] op_sel_hi:[1,0] neg_lo:[0,1] neg_hi:[0,1]
	v_pk_add_f32 v[110:111], v[110:111], v[0:1] op_sel_hi:[1,0] neg_lo:[0,1] neg_hi:[0,1]
	v_pk_add_f32 v[126:127], v[126:127], v[0:1] op_sel_hi:[1,0] neg_lo:[0,1] neg_hi:[0,1]
	v_exp_f32_e64 v0, -v0
	v_xor_b32_e32 v80, 0x80000000, v217
	v_mov_b32_e32 v81, v80
	v_mov_b32_e32 v82, v80
	v_mov_b32_e32 v83, v80
	v_mov_b32_e32 v84, v80
	v_mov_b32_e32 v85, v80
	v_mov_b32_e32 v86, v80
	v_mov_b32_e32 v87, v80
	v_mov_b32_e32 v88, v80
	v_mov_b32_e32 v89, v80
	v_mov_b32_e32 v90, v80
	v_mov_b32_e32 v91, v80
	v_mov_b32_e32 v92, v80
	v_mov_b32_e32 v93, v80
	v_mov_b32_e32 v94, v80
	v_mov_b32_e32 v95, v80
	s_branch .LBB0_615

; #define ATT_TOP(t) do { if ((t) + 2 < NT) ATT_LOADK((t) + 2); if ((t) + 1 < NT) ATT_LOADV((t) + 1); } while (0)
; #define ATT_BOT(t) do { if ((t) + 2 < NT) ATT_STOREK(k2); if ((t) + 1 < NT) ATT_STOREV(v1); __syncthreads(); \
;         { const int kk = k0; k0 = k1; k1 = k2; k2 = kk; const int vv = v0; v0 = v1; v1 = vv; } } while (0)
; #define ATT_RESC() do { if (__any(alpha_n < 1.f)) { _Pragma("unroll") for (int i = 0; i < 4; ++i) _Pragma("unroll") for (int r = 0; r < 16; ++r) o[i][r] *= alpha_n; } } while (0)
; __device__ __forceinline__ void unit(LAS unsigned char* lds, int b, int h, int qb, const bf16_t* Q, const bf16_t* Kn, const bf16_t* Kr, const bf16_t* VT, const bf16_t* proj, bf16_t* ymix, int wv) {
;     ...
;     bf16x8 pf2[2][2]; float alpha_n = 1.f;
;     ...
;     for (; t + 1 < NT - 4; ++t) { ATT_TOP(t); ATT_QKN(k1); __builtin_amdgcn_sched_barrier(0); ATT_FUSED(t + 1, false); ATT_RESC(); ATT_BOT(t); }
;     for (; t + 1 < NT; ++t) { ATT_TOP(t); ATT_QKN(k1); __builtin_amdgcn_sched_barrier(0); ATT_FUSED(t + 1, true); ATT_RESC(); ATT_BOT(t); }
.LBB0_615:
	v_mfma_f32_32x32x16_bf16 v[48:63], v[238:241], v[196:199], v[48:63]
	ds_read2_b64 v[238:241], v229 offset0:40 offset1:42
	v_add_u32_e32 v232, s70, v212
	v_add_u32_e32 v233, s70, v214
	s_waitcnt vmcnt(4)
	ds_write_b128 v232, v[176:179]
	v_exp_f32_e32 v220, v96
	v_exp_f32_e32 v221, v112
	v_exp_f32_e32 v14, v97
	v_exp_f32_e32 v15, v113
	v_mfma_f32_32x32x16_bf16 v[32:47], v[244:247], v[196:199], v[32:47]
	ds_read2_b64 v[244:247], v230 offset0:72 offset1:74
	s_waitcnt vmcnt(3)
	ds_write_b128 v232, v[184:187] offset:12800
	v_exp_f32_e32 v12, v98
	v_exp_f32_e32 v13, v114
	v_exp_f32_e32 v10, v99
	v_exp_f32_e32 v11, v115
	v_mfma_f32_32x32x16_bf16 v[16:31], v[248:251], v[196:199], v[16:31]
	ds_read2_b64 v[248:251], v252 offset0:104 offset1:106
	s_waitcnt vmcnt(2)
	ds_write_b128 v233, v[188:191] offset:256
	v_exp_f32_e32 v98, v100
	v_exp_f32_e32 v99, v116
	v_exp_f32_e32 v96, v101
	v_exp_f32_e32 v97, v117
	v_mfma_f32_32x32x16_bf16 v[64:79], v[234:237], v[192:195], v[64:79]
	ds_read2_b64 v[234:237], v231 offset0:12 offset1:14
	v_exp_f32_e32 v112, v102
	v_exp_f32_e32 v113, v118
	v_exp_f32_e32 v100, v103
	v_exp_f32_e32 v101, v119
	s_waitcnt lgkmcnt(6)
	v_mfma_f32_32x32x16_bf16 v[48:63], v[238:241], v[192:195], v[48:63]
	ds_read2_b64 v[238:241], v229 offset0:44 offset1:46
	v_exp_f32_e32 v114, v104
	v_exp_f32_e32 v115, v120
	v_exp_f32_e32 v102, v105
	v_exp_f32_e32 v103, v121
	s_waitcnt lgkmcnt(5)
	v_mfma_f32_32x32x16_bf16 v[32:47], v[244:247], v[192:195], v[32:47]
	ds_read2_b64 v[244:247], v230 offset0:76 offset1:78
	v_exp_f32_e32 v116, v106
	v_exp_f32_e32 v117, v122
	v_exp_f32_e32 v104, v107
	v_exp_f32_e32 v105, v123
	s_waitcnt lgkmcnt(4)
	v_mfma_f32_32x32x16_bf16 v[16:31], v[248:251], v[192:195], v[16:31]
	ds_read2_b64 v[248:251], v252 offset0:108 offset1:110
	v_exp_f32_e32 v118, v108
	v_exp_f32_e32 v119, v124
	v_exp_f32_e32 v106, v109
	v_exp_f32_e32 v107, v125
	s_waitcnt lgkmcnt(3)
	v_mfma_f32_32x32x16_bf16 v[64:79], v[234:237], v[180:183], v[64:79]
	v_exp_f32_e32 v120, v110
	v_exp_f32_e32 v121, v126
	v_exp_f32_e32 v108, v111
	v_exp_f32_e32 v109, v127
	s_waitcnt lgkmcnt(2)
	v_mfma_f32_32x32x16_bf16 v[48:63], v[238:241], v[180:183], v[48:63]
	v_cvt_pk_bf16_f32 v200, v220, v14
	v_cvt_pk_bf16_f32 v201, v12, v10
	v_cvt_pk_bf16_f32 v202, v98, v96
	v_cvt_pk_bf16_f32 v203, v112, v100
	v_cvt_pk_bf16_f32 v196, v114, v102
	v_cvt_pk_bf16_f32 v197, v116, v104
	v_cvt_pk_bf16_f32 v198, v118, v106
	v_cvt_pk_bf16_f32 v199, v120, v108
	s_waitcnt lgkmcnt(1)
	v_mfma_f32_32x32x16_bf16 v[32:47], v[244:247], v[180:183], v[32:47]
	v_cvt_pk_bf16_f32 v192, v221, v15
	v_cvt_pk_bf16_f32 v193, v13, v11
	v_cvt_pk_bf16_f32 v194, v99, v97
	v_cvt_pk_bf16_f32 v195, v113, v101
	s_waitcnt lgkmcnt(0)
	v_mfma_f32_32x32x16_bf16 v[16:31], v[248:251], v[180:183], v[16:31]
	v_cvt_pk_bf16_f32 v180, v115, v103
	v_cvt_pk_bf16_f32 v181, v117, v105
	v_cvt_pk_bf16_f32 v182, v119, v107
	v_cvt_pk_bf16_f32 v183, v121, v109
	v_cmp_gt_f32_e32 vcc, 1.0, v0
	s_cbranch_vccz .LBB0_617
	v_pk_mul_f32 v[78:79], v[0:1], v[78:79] op_sel_hi:[0,1]
	v_pk_mul_f32 v[76:77], v[0:1], v[76:77] op_sel_hi:[0,1]
	v_pk_mul_f32 v[74:75], v[0:1], v[74:75] op_sel_hi:[0,1]
	v_pk_mul_f32 v[72:73], v[0:1], v[72:73] op_sel_hi:[0,1]
	v_pk_mul_f32 v[70:71], v[0:1], v[70:71] op_sel_hi:[0,1]
	v_pk_mul_f32 v[68:69], v[0:1], v[68:69] op_sel_hi:[0,1]
	v_pk_mul_f32 v[66:67], v[0:1], v[66:67] op_sel_hi:[0,1]
	v_pk_mul_f32 v[64:65], v[0:1], v[64:65] op_sel_hi:[0,1]
	v_pk_mul_f32 v[62:63], v[0:1], v[62:63] op_sel_hi:[0,1]
	v_pk_mul_f32 v[60:61], v[0:1], v[60:61] op_sel_hi:[0,1]
	v_pk_mul_f32 v[58:59], v[0:1], v[58:59] op_sel_hi:[0,1]
	v_pk_mul_f32 v[56:57], v[0:1], v[56:57] op_sel_hi:[0,1]
	v_pk_mul_f32 v[54:55], v[0:1], v[54:55] op_sel_hi:[0,1]
	v_pk_mul_f32 v[52:53], v[0:1], v[52:53] op_sel_hi:[0,1]
	v_pk_mul_f32 v[50:51], v[0:1], v[50:51] op_sel_hi:[0,1]
	v_pk_mul_f32 v[48:49], v[0:1], v[48:49] op_sel_hi:[0,1]
	v_pk_mul_f32 v[46:47], v[0:1], v[46:47] op_sel_hi:[0,1]
	v_pk_mul_f32 v[44:45], v[0:1], v[44:45] op_sel_hi:[0,1]
	v_pk_mul_f32 v[42:43], v[0:1], v[42:43] op_sel_hi:[0,1]
	v_pk_mul_f32 v[40:41], v[0:1], v[40:41] op_sel_hi:[0,1]
	v_pk_mul_f32 v[38:39], v[0:1], v[38:39] op_sel_hi:[0,1]
	v_pk_mul_f32 v[36:37], v[0:1], v[36:37] op_sel_hi:[0,1]
	v_pk_mul_f32 v[34:35], v[0:1], v[34:35] op_sel_hi:[0,1]
	v_pk_mul_f32 v[32:33], v[0:1], v[32:33] op_sel_hi:[0,1]
	v_pk_mul_f32 v[30:31], v[0:1], v[30:31] op_sel_hi:[0,1]
	v_pk_mul_f32 v[28:29], v[0:1], v[28:29] op_sel_hi:[0,1]
	v_pk_mul_f32 v[26:27], v[0:1], v[26:27] op_sel_hi:[0,1]
	v_pk_mul_f32 v[24:25], v[0:1], v[24:25] op_sel_hi:[0,1]
	v_pk_mul_f32 v[22:23], v[0:1], v[22:23] op_sel_hi:[0,1]
	v_pk_mul_f32 v[20:21], v[0:1], v[20:21] op_sel_hi:[0,1]
	v_pk_mul_f32 v[18:19], v[0:1], v[18:19] op_sel_hi:[0,1]
	v_pk_mul_f32 v[16:17], v[0:1], v[16:17] op_sel_hi:[0,1]
.LBB0_617:
	v_pk_add_f32 v[110:111], v[220:221], 0 op_sel_hi:[1,0]
	s_add_i32 s8, s70, 0
	v_pk_add_f32 v[14:15], v[14:15], v[110:111]
	s_add_i32 s55, s55, 1
	v_pk_add_f32 v[12:13], v[12:13], v[14:15]
	s_add_i32 s58, s58, 64
	v_pk_add_f32 v[10:11], v[10:11], v[12:13]
	s_cmp_eq_u32 s63, s55
	v_pk_add_f32 v[10:11], v[98:99], v[10:11]
	s_nop 0
	v_pk_add_f32 v[10:11], v[96:97], v[10:11]
	s_nop 0
	v_pk_add_f32 v[10:11], v[112:113], v[10:11]
	s_nop 0
	v_pk_add_f32 v[10:11], v[100:101], v[10:11]
	s_nop 0
	v_pk_add_f32 v[10:11], v[114:115], v[10:11]
	s_nop 0
	v_pk_add_f32 v[10:11], v[102:103], v[10:11]
	s_nop 0
	v_pk_add_f32 v[10:11], v[116:117], v[10:11]
	s_nop 0
	v_pk_add_f32 v[10:11], v[104:105], v[10:11]
	s_nop 0
	v_pk_add_f32 v[10:11], v[118:119], v[10:11]
	s_nop 0
	v_pk_add_f32 v[10:11], v[106:107], v[10:11]
	s_nop 0
	v_pk_add_f32 v[10:11], v[120:121], v[10:11]
	s_nop 0
	v_pk_add_f32 v[10:11], v[108:109], v[10:11]
	s_nop 0
	v_add_f32_e32 v10, v10, v11
	v_fmac_f32_e32 v10, v228, v0
	v_add_u32_e32 v0, s61, v213
	v_add_u32_e32 v11, 0x2200, v0
	v_mov_b32_e32 v228, v10
	s_waitcnt vmcnt(1)
	ds_write2_b64 v0, v[2:3], v[4:5] offset1:1
	s_waitcnt vmcnt(0)
	ds_write2_b64 v11, v[6:7], v[8:9] offset1:1
	s_waitcnt lgkmcnt(0)
	s_barrier
	s_cbranch_scc1 .LBB0_620
	s_mov_b32 s8, s60
	s_mov_b32 s60, s70
	s_mov_b32 s70, s72
	s_mov_b32 s9, s61
	s_mov_b32 s61, s71
	s_branch .LBB0_612

; __device__ __forceinline__ void unit(LAS unsigned char* lds, int b, int h, int qb, const bf16_t* Q, const bf16_t* Kn, const bf16_t* Kr, const bf16_t* VT, const bf16_t* proj, bf16_t* ymix, int wv) {
;     ...
;     f32x16 o[4];
; #pragma unroll
;     for (int i = 0; i < 4; ++i) o[i] = (f32x16){0, 0, 0, 0, 0, 0, 0, 0, 0, 0, 0, 0, 0, 0, 0, 0};
;     float mrun = -INFINITY, lrun = 0.f;
;     const int qidx = q0 + 32 * wave + l32;
;     f32x16 p0, p1; bf16x8 pf[2][2];
.LBB0_1177:
	s_sub_i32 s6, s36, 32
	s_lshl_b64 s[62:63], s[6:7], 11
	s_mov_b32 s37, s7
	v_lshl_add_u64 v[232:233], v[208:209], 0, s[62:63]
	s_lshl_b64 s[62:63], s[36:37], 11
	global_load_dwordx4 v[176:179], v[232:233], off
	v_lshl_add_u64 v[232:233], v[208:209], 0, s[62:63]
	s_lshl_b64 s[62:63], s[6:7], 7
	global_load_dwordx4 v[180:183], v[232:233], off
	v_lshl_add_u64 v[232:233], v[210:211], 0, s[62:63]
	global_load_dwordx4 v[184:187], v[232:233], off
	v_add_u32_e32 v0, s38, v215
	ds_read_b128 v[2:5], v0
	ds_read_b128 v[6:9], v0 offset:32
	v_mov_b64_e32 v[126:127], v[94:95]
	v_mov_b64_e32 v[124:125], v[92:93]
	v_mov_b64_e32 v[122:123], v[90:91]
	s_waitcnt lgkmcnt(1)
	v_mfma_f32_32x32x16_bf16 v[96:111], v[2:5], v[128:131], v[80:95]
	ds_read_b128 v[2:5], v0 offset:12800
	ds_read_b128 v[10:13], v0 offset:12832
	v_mov_b64_e32 v[120:121], v[88:89]
	v_mov_b64_e32 v[118:119], v[86:87]
	v_mov_b64_e32 v[116:117], v[84:85]
	v_mov_b64_e32 v[114:115], v[82:83]
	v_mov_b64_e32 v[112:113], v[80:81]
	s_waitcnt lgkmcnt(2)
	v_mfma_f32_32x32x16_bf16 v[96:111], v[6:9], v[132:135], v[96:111]
	s_mov_b32 s58, s59
	s_mov_b32 s59, s60
	s_waitcnt lgkmcnt(1)
	v_mfma_f32_32x32x16_bf16 v[112:127], v[2:5], v[128:131], v[112:127]
	ds_read_b128 v[2:5], v0 offset:64
	ds_read_b128 v[6:9], v0 offset:96
	s_waitcnt lgkmcnt(2)
	v_mfma_f32_32x32x16_bf16 v[112:127], v[10:13], v[132:135], v[112:127]
	s_waitcnt lgkmcnt(1)
	v_mfma_f32_32x32x16_bf16 v[96:111], v[2:5], v[136:139], v[96:111]
	ds_read_b128 v[2:5], v0 offset:12864
	ds_read_b128 v[10:13], v0 offset:12896
	s_waitcnt lgkmcnt(1)
	v_mfma_f32_32x32x16_bf16 v[112:127], v[2:5], v[136:139], v[112:127]
	v_mfma_f32_32x32x16_bf16 v[96:111], v[6:9], v[140:143], v[96:111]
	ds_read_b128 v[2:5], v0 offset:128
	ds_read_b128 v[6:9], v0 offset:160
	s_waitcnt lgkmcnt(2)
	v_mfma_f32_32x32x16_bf16 v[112:127], v[10:13], v[140:143], v[112:127]
	s_waitcnt lgkmcnt(1)
	v_mfma_f32_32x32x16_bf16 v[96:111], v[2:5], v[144:147], v[96:111]
	ds_read_b128 v[2:5], v0 offset:12928
	ds_read_b128 v[10:13], v0 offset:12960
	s_waitcnt lgkmcnt(1)
	v_mfma_f32_32x32x16_bf16 v[112:127], v[2:5], v[144:147], v[112:127]
	v_mfma_f32_32x32x16_bf16 v[96:111], v[6:9], v[148:151], v[96:111]
	ds_read_b128 v[2:5], v0 offset:192
	ds_read_b128 v[6:9], v0 offset:224
	s_waitcnt lgkmcnt(2)
	v_mfma_f32_32x32x16_bf16 v[112:127], v[10:13], v[148:151], v[112:127]
	s_waitcnt lgkmcnt(1)
	v_mfma_f32_32x32x16_bf16 v[96:111], v[2:5], v[152:155], v[96:111]
	ds_read_b128 v[2:5], v0 offset:12992
	ds_read_b128 v[10:13], v0 offset:13024
	s_waitcnt lgkmcnt(1)
	v_mfma_f32_32x32x16_bf16 v[112:127], v[2:5], v[152:155], v[112:127]
	v_mfma_f32_32x32x16_bf16 v[96:111], v[6:9], v[156:159], v[96:111]
	ds_read_b128 v[2:5], v0 offset:256
	ds_read_b128 v[6:9], v0 offset:288
	s_waitcnt lgkmcnt(2)
	v_mfma_f32_32x32x16_bf16 v[112:127], v[10:13], v[156:159], v[112:127]
	s_waitcnt lgkmcnt(1)
	v_mfma_f32_32x32x16_bf16 v[96:111], v[2:5], v[160:163], v[96:111]
	ds_read_b128 v[2:5], v0 offset:13056
	ds_read_b128 v[10:13], v0 offset:13088
	s_waitcnt lgkmcnt(1)
	v_mfma_f32_32x32x16_bf16 v[112:127], v[2:5], v[160:163], v[112:127]
	ds_read_b128 v[2:5], v0 offset:320
	v_mfma_f32_32x32x16_bf16 v[96:111], v[6:9], v[164:167], v[96:111]
	s_waitcnt lgkmcnt(1)
	v_mfma_f32_32x32x16_bf16 v[112:127], v[10:13], v[164:167], v[112:127]
	ds_read_b128 v[6:9], v0 offset:13120
	ds_read_b128 v[10:13], v0 offset:352
	s_waitcnt lgkmcnt(2)
	v_mfma_f32_32x32x16_bf16 v[96:111], v[2:5], v[168:171], v[96:111]
	s_add_i32 s6, s36, 0xffffffa0
	ds_read_b128 v[230:233], v0 offset:13152
	s_waitcnt lgkmcnt(2)
	v_mfma_f32_32x32x16_bf16 v[112:127], v[6:9], v[168:171], v[112:127]
	s_lshl_b64 s[62:63], s[6:7], 1
	v_lshl_add_u64 v[8:9], v[218:219], 0, s[62:63]
	v_lshl_add_u64 v[2:3], v[206:207], 0, s[62:63]
	global_load_dwordx4 v[2:5], v[2:3], off
	s_nop 0
	s_nop 0
	global_load_dwordx4 v[6:9], v[8:9], off
	s_waitcnt lgkmcnt(1)
	v_mfma_f32_32x32x16_bf16 v[96:111], v[10:13], v[172:175], v[96:111]
	s_waitcnt lgkmcnt(0)
	v_mfma_f32_32x32x16_bf16 v[112:127], v[230:233], v[172:175], v[112:127]
	s_add_i32 s6, s58, 0
	s_add_i32 s6, s6, 0x12c00
	v_add_u32_e32 v0, s6, v227
	v_add_u32_e32 v231, v0, v226
	v_add_u32_e32 v229, 0x1000, v231
	v_add_u32_e32 v230, 0x2000, v231
	v_add_u32_e32 v252, 0x3000, v231
	ds_read2_b64 v[234:237], v231 offset1:2
	ds_read2_b64 v[238:241], v229 offset0:32 offset1:34
	ds_read2_b64 v[244:247], v230 offset0:64 offset1:66
	ds_read2_b64 v[248:251], v252 offset0:96 offset1:98
	s_nop 2
	v_max_f32_e32 v0, v96, v96
	v_max_f32_e32 v0, 0xff800000, v0
	v_max3_f32 v0, v0, v97, v98
	s_waitcnt lgkmcnt(3)
	v_mfma_f32_32x32x16_bf16 v[64:79], v[234:237], v[200:203], v[64:79]
	ds_read2_b64 v[234:237], v231 offset0:4 offset1:6
	v_max3_f32 v10, v112, s52, v113
	v_max3_f32 v14, v10, v114, v115
	s_waitcnt lgkmcnt(3)
	v_mfma_f32_32x32x16_bf16 v[48:63], v[238:241], v[200:203], v[48:63]
	ds_read2_b64 v[238:241], v229 offset0:36 offset1:38
	v_max3_f32 v0, v0, v99, v100
	v_max3_f32 v14, v14, v116, v117
	v_max3_f32 v0, v0, v101, v102
	v_max3_f32 v14, v14, v118, v119
	s_waitcnt lgkmcnt(3)
	v_mfma_f32_32x32x16_bf16 v[32:47], v[244:247], v[200:203], v[32:47]
	ds_read2_b64 v[244:247], v230 offset0:68 offset1:70
	v_max3_f32 v0, v0, v103, v104
	v_max3_f32 v14, v14, v120, v121
	v_max3_f32 v0, v0, v105, v106
	v_max3_f32 v14, v14, v122, v123
	s_waitcnt lgkmcnt(3)
	v_mfma_f32_32x32x16_bf16 v[16:31], v[248:251], v[200:203], v[16:31]
	ds_read2_b64 v[248:251], v252 offset0:100 offset1:102
	v_max3_f32 v0, v0, v107, v108
	v_max3_f32 v10, v14, v124, v125
	v_max3_f32 v0, v0, v109, v110
	v_max3_f32 v14, v10, v126, v127
	v_max3_f32 v0, v0, v111, v14
	v_mov_b32_e32 v14, v222
	s_waitcnt lgkmcnt(3)
	v_mfma_f32_32x32x16_bf16 v[64:79], v[234:237], v[196:199], v[64:79]
	ds_read2_b64 v[234:237], v231 offset0:8 offset1:10
	v_lshlrev_b32_e32 v14, 2, v14
	v_xor_b32_e32 v14, 0x80, v14
	ds_bpermute_b32 v14, v14, v0
	s_waitcnt lgkmcnt(0)
	v_max_f32_e32 v14, v14, v14
	v_max_f32_e32 v0, v0, v14
	v_cmp_lt_f32_e32 vcc, s53, v0
	s_cbranch_vccz .LBB0_1179
	v_max_f32_e32 v0, v0, v0
	v_max_f32_e32 v0, 0, v0
	v_add_f32_e32 v217, v217, v0
	v_pk_add_f32 v[96:97], v[96:97], v[0:1] op_sel_hi:[1,0] neg_lo:[0,1] neg_hi:[0,1]
	v_pk_add_f32 v[112:113], v[112:113], v[0:1] op_sel_hi:[1,0] neg_lo:[0,1] neg_hi:[0,1]
	v_pk_add_f32 v[98:99], v[98:99], v[0:1] op_sel_hi:[1,0] neg_lo:[0,1] neg_hi:[0,1]
	v_pk_add_f32 v[114:115], v[114:115], v[0:1] op_sel_hi:[1,0] neg_lo:[0,1] neg_hi:[0,1]
	v_pk_add_f32 v[100:101], v[100:101], v[0:1] op_sel_hi:[1,0] neg_lo:[0,1] neg_hi:[0,1]
	v_pk_add_f32 v[116:117], v[116:117], v[0:1] op_sel_hi:[1,0] neg_lo:[0,1] neg_hi:[0,1]
	v_pk_add_f32 v[102:103], v[102:103], v[0:1] op_sel_hi:[1,0] neg_lo:[0,1] neg_hi:[0,1]
	v_pk_add_f32 v[118:119], v[118:119], v[0:1] op_sel_hi:[1,0] neg_lo:[0,1] neg_hi:[0,1]
	v_pk_add_f32 v[104:105], v[104:105], v[0:1] op_sel_hi:[1,0] neg_lo:[0,1] neg_hi:[0,1]
	v_pk_add_f32 v[120:121], v[120:121], v[0:1] op_sel_hi:[1,0] neg_lo:[0,1] neg_hi:[0,1]
	v_pk_add_f32 v[106:107], v[106:107], v[0:1] op_sel_hi:[1,0] neg_lo:[0,1] neg_hi:[0,1]
	v_pk_add_f32 v[122:123], v[122:123], v[0:1] op_sel_hi:[1,0] neg_lo:[0,1] neg_hi:[0,1]
	v_pk_add_f32 v[108:109], v[108:109], v[0:1] op_sel_hi:[1,0] neg_lo:[0,1] neg_hi:[0,1]
	v_pk_add_f32 v[124:125], v[124:125], v[0:1] op_sel_hi:[1,0] neg_lo:[0,1] neg_hi:[0,1]
	v_pk_add_f32 v[110:111], v[110:111], v[0:1] op_sel_hi:[1,0] neg_lo:[0,1] neg_hi:[0,1]
	v_pk_add_f32 v[126:127], v[126:127], v[0:1] op_sel_hi:[1,0] neg_lo:[0,1] neg_hi:[0,1]
	v_exp_f32_e64 v0, -v0
	v_xor_b32_e32 v80, 0x80000000, v217
	v_mov_b32_e32 v81, v80
	v_mov_b32_e32 v82, v80
	v_mov_b32_e32 v83, v80
	v_mov_b32_e32 v84, v80
	v_mov_b32_e32 v85, v80
	v_mov_b32_e32 v86, v80
	v_mov_b32_e32 v87, v80
	v_mov_b32_e32 v88, v80
	v_mov_b32_e32 v89, v80
	v_mov_b32_e32 v90, v80
	v_mov_b32_e32 v91, v80
	v_mov_b32_e32 v92, v80
	v_mov_b32_e32 v93, v80
	v_mov_b32_e32 v94, v80
	v_mov_b32_e32 v95, v80
	s_branch .LBB0_1180

; #define ATT_TOP(t) do { if ((t) + 2 < NT) ATT_LOADK((t) + 2); if ((t) + 1 < NT) ATT_LOADV((t) + 1); } while (0)
; #define ATT_BOT(t) do { if ((t) + 2 < NT) ATT_STOREK(k2); if ((t) + 1 < NT) ATT_STOREV(v1); __syncthreads(); \
;         { const int kk = k0; k0 = k1; k1 = k2; k2 = kk; const int vv = v0; v0 = v1; v1 = vv; } } while (0)
; #define ATT_RESC() do { if (__any(alpha_n < 1.f)) { _Pragma("unroll") for (int i = 0; i < 4; ++i) _Pragma("unroll") for (int r = 0; r < 16; ++r) o[i][r] *= alpha_n; } } while (0)
; __device__ __forceinline__ void unit(LAS unsigned char* lds, int b, int h, int qb, const bf16_t* Q, const bf16_t* Kn, const bf16_t* Kr, const bf16_t* VT, const bf16_t* proj, bf16_t* ymix, int wv) {
;     ...
;     bf16x8 pf2[2][2]; float alpha_n = 1.f;
;     ...
;     for (; t + 1 < NT - 4; ++t) { ATT_TOP(t); ATT_QKN(k1); __builtin_amdgcn_sched_barrier(0); ATT_FUSED(t + 1, false); ATT_RESC(); ATT_BOT(t); }
;     for (; t + 1 < NT; ++t) { ATT_TOP(t); ATT_QKN(k1); __builtin_amdgcn_sched_barrier(0); ATT_FUSED(t + 1, true); ATT_RESC(); ATT_BOT(t); }
.LBB0_1180:
	v_mfma_f32_32x32x16_bf16 v[48:63], v[238:241], v[196:199], v[48:63]
	ds_read2_b64 v[238:241], v229 offset0:40 offset1:42
	v_add_u32_e32 v232, s57, v212
	v_add_u32_e32 v233, s57, v214
	s_waitcnt vmcnt(4)
	ds_write_b128 v232, v[176:179]
	v_exp_f32_e32 v220, v96
	v_exp_f32_e32 v221, v112
	v_exp_f32_e32 v14, v97
	v_exp_f32_e32 v15, v113
	v_mfma_f32_32x32x16_bf16 v[32:47], v[244:247], v[196:199], v[32:47]
	ds_read2_b64 v[244:247], v230 offset0:72 offset1:74
	s_waitcnt vmcnt(3)
	ds_write_b128 v232, v[180:183] offset:12800
	v_exp_f32_e32 v12, v98
	v_exp_f32_e32 v13, v114
	v_exp_f32_e32 v10, v99
	v_exp_f32_e32 v11, v115
	v_mfma_f32_32x32x16_bf16 v[16:31], v[248:251], v[196:199], v[16:31]
	ds_read2_b64 v[248:251], v252 offset0:104 offset1:106
	s_waitcnt vmcnt(2)
	ds_write_b128 v233, v[184:187] offset:256
	v_exp_f32_e32 v98, v100
	v_exp_f32_e32 v99, v116
	v_exp_f32_e32 v96, v101
	v_exp_f32_e32 v97, v117
	v_mfma_f32_32x32x16_bf16 v[64:79], v[234:237], v[192:195], v[64:79]
	ds_read2_b64 v[234:237], v231 offset0:12 offset1:14
	v_exp_f32_e32 v112, v102
	v_exp_f32_e32 v113, v118
	v_exp_f32_e32 v100, v103
	v_exp_f32_e32 v101, v119
	s_waitcnt lgkmcnt(6)
	v_mfma_f32_32x32x16_bf16 v[48:63], v[238:241], v[192:195], v[48:63]
	ds_read2_b64 v[238:241], v229 offset0:44 offset1:46
	v_exp_f32_e32 v114, v104
	v_exp_f32_e32 v115, v120
	v_exp_f32_e32 v102, v105
	v_exp_f32_e32 v103, v121
	s_waitcnt lgkmcnt(5)
	v_mfma_f32_32x32x16_bf16 v[32:47], v[244:247], v[192:195], v[32:47]
	ds_read2_b64 v[244:247], v230 offset0:76 offset1:78
	v_exp_f32_e32 v116, v106
	v_exp_f32_e32 v117, v122
	v_exp_f32_e32 v104, v107
	v_exp_f32_e32 v105, v123
	s_waitcnt lgkmcnt(4)
	v_mfma_f32_32x32x16_bf16 v[16:31], v[248:251], v[192:195], v[16:31]
	ds_read2_b64 v[248:251], v252 offset0:108 offset1:110
	v_exp_f32_e32 v118, v108
	v_exp_f32_e32 v119, v124
	v_exp_f32_e32 v106, v109
	v_exp_f32_e32 v107, v125
	s_waitcnt lgkmcnt(3)
	v_mfma_f32_32x32x16_bf16 v[64:79], v[234:237], v[188:191], v[64:79]
	v_exp_f32_e32 v120, v110
	v_exp_f32_e32 v121, v126
	v_exp_f32_e32 v108, v111
	v_exp_f32_e32 v109, v127
	s_waitcnt lgkmcnt(2)
	v_mfma_f32_32x32x16_bf16 v[48:63], v[238:241], v[188:191], v[48:63]
	v_cvt_pk_bf16_f32 v200, v220, v14
	v_cvt_pk_bf16_f32 v201, v12, v10
	v_cvt_pk_bf16_f32 v202, v98, v96
	v_cvt_pk_bf16_f32 v203, v112, v100
	v_cvt_pk_bf16_f32 v196, v114, v102
	v_cvt_pk_bf16_f32 v197, v116, v104
	v_cvt_pk_bf16_f32 v198, v118, v106
	v_cvt_pk_bf16_f32 v199, v120, v108
	s_waitcnt lgkmcnt(1)
	v_mfma_f32_32x32x16_bf16 v[32:47], v[244:247], v[188:191], v[32:47]
	v_cvt_pk_bf16_f32 v192, v221, v15
	v_cvt_pk_bf16_f32 v193, v13, v11
	v_cvt_pk_bf16_f32 v194, v99, v97
	v_cvt_pk_bf16_f32 v195, v113, v101
	s_waitcnt lgkmcnt(0)
	v_mfma_f32_32x32x16_bf16 v[16:31], v[248:251], v[188:191], v[16:31]
	v_cvt_pk_bf16_f32 v188, v115, v103
	v_cvt_pk_bf16_f32 v189, v117, v105
	v_cvt_pk_bf16_f32 v190, v119, v107
	v_cvt_pk_bf16_f32 v191, v121, v109
	v_cmp_gt_f32_e32 vcc, 1.0, v0
	s_cbranch_vccz .LBB0_1182
	v_pk_mul_f32 v[78:79], v[0:1], v[78:79] op_sel_hi:[0,1]
	v_pk_mul_f32 v[76:77], v[0:1], v[76:77] op_sel_hi:[0,1]
	v_pk_mul_f32 v[74:75], v[0:1], v[74:75] op_sel_hi:[0,1]
	v_pk_mul_f32 v[72:73], v[0:1], v[72:73] op_sel_hi:[0,1]
	v_pk_mul_f32 v[70:71], v[0:1], v[70:71] op_sel_hi:[0,1]
	v_pk_mul_f32 v[68:69], v[0:1], v[68:69] op_sel_hi:[0,1]
	v_pk_mul_f32 v[66:67], v[0:1], v[66:67] op_sel_hi:[0,1]
	v_pk_mul_f32 v[64:65], v[0:1], v[64:65] op_sel_hi:[0,1]
	v_pk_mul_f32 v[62:63], v[0:1], v[62:63] op_sel_hi:[0,1]
	v_pk_mul_f32 v[60:61], v[0:1], v[60:61] op_sel_hi:[0,1]
	v_pk_mul_f32 v[58:59], v[0:1], v[58:59] op_sel_hi:[0,1]
	v_pk_mul_f32 v[56:57], v[0:1], v[56:57] op_sel_hi:[0,1]
	v_pk_mul_f32 v[54:55], v[0:1], v[54:55] op_sel_hi:[0,1]
	v_pk_mul_f32 v[52:53], v[0:1], v[52:53] op_sel_hi:[0,1]
	v_pk_mul_f32 v[50:51], v[0:1], v[50:51] op_sel_hi:[0,1]
	v_pk_mul_f32 v[48:49], v[0:1], v[48:49] op_sel_hi:[0,1]
	v_pk_mul_f32 v[46:47], v[0:1], v[46:47] op_sel_hi:[0,1]
	v_pk_mul_f32 v[44:45], v[0:1], v[44:45] op_sel_hi:[0,1]
	v_pk_mul_f32 v[42:43], v[0:1], v[42:43] op_sel_hi:[0,1]
	v_pk_mul_f32 v[40:41], v[0:1], v[40:41] op_sel_hi:[0,1]
	v_pk_mul_f32 v[38:39], v[0:1], v[38:39] op_sel_hi:[0,1]
	v_pk_mul_f32 v[36:37], v[0:1], v[36:37] op_sel_hi:[0,1]
	v_pk_mul_f32 v[34:35], v[0:1], v[34:35] op_sel_hi:[0,1]
	v_pk_mul_f32 v[32:33], v[0:1], v[32:33] op_sel_hi:[0,1]
	v_pk_mul_f32 v[30:31], v[0:1], v[30:31] op_sel_hi:[0,1]
	v_pk_mul_f32 v[28:29], v[0:1], v[28:29] op_sel_hi:[0,1]
	v_pk_mul_f32 v[26:27], v[0:1], v[26:27] op_sel_hi:[0,1]
	v_pk_mul_f32 v[24:25], v[0:1], v[24:25] op_sel_hi:[0,1]
	v_pk_mul_f32 v[22:23], v[0:1], v[22:23] op_sel_hi:[0,1]
	v_pk_mul_f32 v[20:21], v[0:1], v[20:21] op_sel_hi:[0,1]
	v_pk_mul_f32 v[18:19], v[0:1], v[18:19] op_sel_hi:[0,1]
	v_pk_mul_f32 v[16:17], v[0:1], v[16:17] op_sel_hi:[0,1]
.LBB0_1182:
	v_pk_add_f32 v[110:111], v[220:221], 0 op_sel_hi:[1,0]
	s_add_i32 s6, s57, 0
	v_pk_add_f32 v[14:15], v[14:15], v[110:111]
	s_add_i32 s17, s17, 1
	v_pk_add_f32 v[12:13], v[12:13], v[14:15]
	s_add_i32 s36, s36, 64
	v_pk_add_f32 v[10:11], v[10:11], v[12:13]
	s_cmp_eq_u32 s41, s17
	v_pk_add_f32 v[10:11], v[98:99], v[10:11]
	s_nop 0
	v_pk_add_f32 v[10:11], v[96:97], v[10:11]
	s_nop 0
	v_pk_add_f32 v[10:11], v[112:113], v[10:11]
	s_nop 0
	v_pk_add_f32 v[10:11], v[100:101], v[10:11]
	s_nop 0
	v_pk_add_f32 v[10:11], v[114:115], v[10:11]
	s_nop 0
	v_pk_add_f32 v[10:11], v[102:103], v[10:11]
	s_nop 0
	v_pk_add_f32 v[10:11], v[116:117], v[10:11]
	s_nop 0
	v_pk_add_f32 v[10:11], v[104:105], v[10:11]
	s_nop 0
	v_pk_add_f32 v[10:11], v[118:119], v[10:11]
	s_nop 0
	v_pk_add_f32 v[10:11], v[106:107], v[10:11]
	s_nop 0
	v_pk_add_f32 v[10:11], v[120:121], v[10:11]
	s_nop 0
	v_pk_add_f32 v[10:11], v[108:109], v[10:11]
	s_nop 0
	v_add_f32_e32 v10, v10, v11
	v_fmac_f32_e32 v10, v228, v0
	v_add_u32_e32 v0, s39, v213
	v_add_u32_e32 v11, 0x2200, v0
	v_mov_b32_e32 v228, v10
	s_waitcnt vmcnt(1)
	ds_write2_b64 v0, v[2:3], v[4:5] offset1:1
	s_waitcnt vmcnt(0)
	ds_write2_b64 v11, v[6:7], v[8:9] offset1:1
	s_waitcnt lgkmcnt(0)
	s_barrier
	s_cbranch_scc1 .LBB0_1185
	s_mov_b32 s60, s38
	s_mov_b32 s38, s57
	s_mov_b32 s57, s59
	s_mov_b32 s59, s39
	s_mov_b32 s39, s58
	s_branch .LBB0_1177
